# speedup vs baseline: 1.0050x; 1.0050x over previous
; __device__ __forceinline__ int tidx() { int t = threadIdx.x; asm volatile("" : "+v"(t)); return t; }
; __device__ __forceinline__ int bidx() { int t = blockIdx.x; asm volatile("" : "+s"(t)); return t; }
; __device__ __forceinline__ void ln_phase(const h16* V, float* X, h16* Xh, const float* g, const float* b, bool final_out, bool dry = false) {
;   const int tid__ = tidx(); const int lane = tid__ & 63, wid = tid__ >> 6;
;   for (int row = bidx() * 4 + wid; row < T_; row += gridDim.x * 4) {
;     const h16* vr = V + (size_t)row * 1024;
;     f4 v[4];
;     float s = 0.f;
; #pragma unroll
;     for (int i = 0; i < 4; ++i) {
;       h4 hv = *(const h4*)(vr + i * 256 + lane * 4);
;       v[i][0] = (float)hv[0]; v[i][1] = (float)hv[1]; v[i][2] = (float)hv[2]; v[i][3] = (float)hv[3];
;       s += v[i][0] + v[i][1] + v[i][2] + v[i][3];
;     }
;     for (int o = 32; o > 0; o >>= 1) s += __shfl_xor(s, o);
;     const float mu = s * (1.f / 1024.f);
.LBB0_1191:
	s_or_b64 exec, exec, s[0:1]
	v_readlane_b32 s0, v248, 54
	v_readlane_b32 s8, v248, 62
	v_readlane_b32 s9, v248, 63
	v_readlane_b32 s10, v247, 0
	v_readlane_b32 s11, v247, 1
	v_readlane_b32 s8, v248, 0
	v_readlane_b32 s1, v248, 55
	v_readlane_b32 s4, v248, 58
	v_readlane_b32 s5, v248, 59
	v_readlane_b32 s6, v248, 60
	v_readlane_b32 s7, v248, 61
	v_readlane_b32 s14, v247, 4
	v_readlane_b32 s15, v247, 5
	v_readlane_b32 s9, v248, 1
	s_mov_b64 s[4:5], s[14:15]
	v_readlane_b32 s0, v247, 46
	s_mov_b64 s[6:7], s[8:9]
	v_mov_b32_e32 v0, v180
	s_barrier
	s_mul_i32 s16, s0, 0xc00
	s_mov_b32 s0, s86
	v_ashrrev_i32_e32 v2, 6, v0
	s_add_u32 s34, s58, 0x9100000
	s_addc_u32 s35, s59, 0
	v_lshl_add_u32 v2, s0, 2, v2
	v_readlane_b32 s2, v248, 56
	v_readlane_b32 s1, v247, 47
	v_cmp_gt_i32_e32 vcc, s84, v2
	v_readlane_b32 s3, v248, 57
	v_readlane_b32 s12, v247, 2
	v_readlane_b32 s13, v247, 3
	v_readlane_b32 s10, v248, 2
	v_readlane_b32 s11, v248, 3
	v_lshlrev_b32_e32 v18, 4, v180
	ds_write_b128 v18, v[60:63]
	ds_write_b128 v18, v[64:67] offset:4096
	ds_write_b128 v18, v[68:71] offset:8192
	ds_write_b128 v18, v[72:75] offset:12288
	ds_write_b128 v18, v[76:79] offset:16384
	ds_write_b128 v18, v[80:83] offset:20480
	ds_write_b128 v18, v[84:87] offset:24576
	ds_write_b128 v18, v[88:91] offset:28672
	s_and_saveexec_b64 s[0:1], vcc
	s_mov_b32 s2, 0x800000
	s_cbranch_execz .LBB0_1194
	v_and_b32_e32 v6, 64, v230
	v_add_u32_e32 v6, 64, v6
	v_xor_b32_e32 v7, 32, v230
	v_cmp_lt_i32_e32 vcc, v7, v6
	s_mov_b32 s17, s89
	s_lshl_b64 s[8:9], s[16:17], 2
	v_cndmask_b32_e32 v7, v230, v7, vcc
	v_lshlrev_b32_e32 v12, 2, v7
	v_xor_b32_e32 v7, 16, v230
	v_cmp_lt_i32_e32 vcc, v7, v6
	s_add_u32 s6, s6, s8
	s_addc_u32 s7, s7, s9
	v_cndmask_b32_e32 v7, v230, v7, vcc
	v_lshlrev_b32_e32 v13, 2, v7
	v_xor_b32_e32 v7, 8, v230
	v_cmp_lt_i32_e32 vcc, v7, v6
	v_lshlrev_b32_e32 v0, 2, v0
	s_add_u32 s4, s4, s8
	v_cndmask_b32_e32 v7, v230, v7, vcc
	v_lshlrev_b32_e32 v14, 2, v7
	v_xor_b32_e32 v7, 4, v230
	v_cmp_lt_i32_e32 vcc, v7, v6
	v_and_b32_e32 v3, 0xfc, v0
	s_addc_u32 s5, s5, s9
	v_cndmask_b32_e32 v7, v230, v7, vcc
	v_lshlrev_b32_e32 v15, 2, v7
	v_xor_b32_e32 v7, 2, v230
	v_cmp_lt_i32_e32 vcc, v7, v6
	v_lshlrev_b32_e32 v8, 2, v3
	v_mov_b32_e32 v9, v1
	v_cndmask_b32_e32 v7, v230, v7, vcc
	v_lshlrev_b32_e32 v16, 2, v7
	v_xor_b32_e32 v7, 1, v230
	v_cmp_lt_i32_e32 vcc, v7, v6
	v_lshlrev_b32_e32 v0, 1, v3
	s_movk_i32 s3, 0x3fff
	v_cndmask_b32_e32 v6, v230, v7, vcc
	v_lshlrev_b32_e32 v17, 2, v6
	v_lshl_add_u64 v[6:7], s[4:5], 0, v[8:9]
	v_readlane_b32 s4, v247, 48
	v_readlane_b32 s5, v247, 49
	v_lshl_add_u64 v[4:5], s[34:35], 0, v[0:1]
	v_lshl_add_u64 v[8:9], s[6:7], 0, v[8:9]
	v_lshl_add_u64 v[10:11], s[4:5], 0, v[0:1]
	s_mov_b64 s[4:5], 0
	global_load_dwordx4 v[60:63], v[6:7], off
	global_load_dwordx4 v[64:67], v[6:7], off offset:1024
	global_load_dwordx4 v[68:71], v[6:7], off offset:2048
	global_load_dwordx4 v[72:75], v[6:7], off offset:3072
	global_load_dwordx4 v[76:79], v[8:9], off
	global_load_dwordx4 v[80:83], v[8:9], off offset:1024
	global_load_dwordx4 v[84:87], v[8:9], off offset:2048
	global_load_dwordx4 v[88:91], v[8:9], off offset:3072
	s_waitcnt vmcnt(0)
.LBB0_1193:
	v_ashrrev_i32_e32 v3, 31, v2
	v_lshlrev_b64 v[26:27], 11, v[2:3]
	v_lshl_add_u64 v[18:19], v[4:5], 0, v[26:27]
	global_load_dwordx2 v[20:21], v[18:19], off offset:1536
	global_load_dwordx2 v[22:23], v[18:19], off offset:1024
	global_load_dwordx2 v[24:25], v[18:19], off
	s_nop 0
	global_load_dwordx2 v[18:19], v[18:19], off offset:512
	v_mov_b32_e32 v28, v1
	v_lshl_add_u64 v[26:27], v[10:11], 0, v[26:27]
	v_add_u32_e32 v2, s77, v2
	s_waitcnt vmcnt(3)
	v_cvt_f32_f16_e32 v31, v20
	s_waitcnt vmcnt(2)
	v_cvt_f32_f16_e32 v30, v22
	s_waitcnt vmcnt(1)
	v_cvt_f32_f16_sdwa v39, v24 dst_sel:DWORD dst_unused:UNUSED_PAD src0_sel:WORD_1
	v_cvt_f32_f16_e32 v38, v24
	v_cvt_f32_f16_e32 v40, v25
	s_waitcnt vmcnt(0)
; __device__ __forceinline__ void ln_phase(const h16* V, float* X, h16* Xh, const float* g, const float* b, bool final_out, bool dry = false) {
;     ...
;     for (int o = 32; o > 0; o >>= 1) s += __shfl_xor(s, o);
;     const float mu = s * (1.f / 1024.f);
;     float q = 0.f;
; #pragma unroll
;     for (int i = 0; i < 4; ++i)
; #pragma unroll
;       for (int j = 0; j < 4; ++j) { float d = v[i][j] - mu; q += d * d; }
;     for (int o = 32; o > 0; o >>= 1) q += __shfl_xor(q, o);
;     const float rs = rsqrtf(q * (1.f / 1024.f) + 1e-5f);
;     if (dry && rs != 12345.678f) continue;
; #pragma unroll
;     for (int i = 0; i < 4; ++i) {
;       int c = i * 256 + lane * 4;
;       f4 gg = *(const f4*)(g + c), bb = *(const f4*)(b + c), o;
;       h4 oh;
; #pragma unroll
;       for (int j = 0; j < 4; ++j) { o[j] = (v[i][j] - mu) * rs * gg[j] + bb[j]; oh[j] = (h16)o[j]; }
;       if (final_out) *(f4*)(X + (size_t)row * 1024 + c) = o;
;       else *(h4*)(Xh + (size_t)row * 1024 + c) = oh;
;     }
	v_cvt_f32_f16_e32 v42, v18
	v_cvt_f32_f16_sdwa v43, v18 dst_sel:DWORD dst_unused:UNUSED_PAD src0_sel:WORD_1
	v_cvt_f32_f16_sdwa v41, v25 dst_sel:DWORD dst_unused:UNUSED_PAD src0_sel:WORD_1
	v_cvt_f32_f16_e32 v44, v19
	v_cvt_f32_f16_sdwa v45, v19 dst_sel:DWORD dst_unused:UNUSED_PAD src0_sel:WORD_1
	v_cvt_f32_f16_sdwa v33, v20 dst_sel:DWORD dst_unused:UNUSED_PAD src0_sel:WORD_1
	v_cvt_f32_f16_sdwa v32, v22 dst_sel:DWORD dst_unused:UNUSED_PAD src0_sel:WORD_1
	v_mov_b32_e32 v0, v39
	v_cvt_f32_f16_e32 v35, v21
	v_cvt_f32_f16_e32 v34, v23
	v_pk_add_f32 v[24:25], v[0:1], v[38:39]
	v_cvt_f32_f16_sdwa v37, v21 dst_sel:DWORD dst_unused:UNUSED_PAD src0_sel:WORD_1
	v_cvt_f32_f16_sdwa v36, v23 dst_sel:DWORD dst_unused:UNUSED_PAD src0_sel:WORD_1
	v_mov_b32_e32 v20, v40
	v_mov_b32_e32 v21, v43
	v_mov_b32_e32 v25, v42
	v_pk_mov_b32 v[22:23], v[40:41], v[44:45] op_sel:[1,0]
	v_pk_add_f32 v[20:21], v[24:25], v[20:21]
	v_pk_add_f32 v[18:19], v[30:31], v[32:33]
	v_mov_b32_e32 v29, v45
	v_pk_add_f32 v[20:21], v[20:21], v[22:23]
	v_pk_add_f32 v[18:19], v[18:19], v[34:35]
	v_pk_add_f32 v[20:21], v[20:21], v[28:29]
	v_pk_add_f32 v[18:19], v[18:19], v[36:37]
	v_add_f32_e32 v0, v20, v21
	v_add_f32_e32 v0, v0, v18
	v_add_f32_e32 v0, v0, v19
	s_nop 1
	v_add_f32_dpp v0, v0, v0 quad_perm:[1,0,3,2] row_mask:0xf bank_mask:0xf bound_ctrl:1
	s_nop 1
	v_add_f32_dpp v0, v0, v0 quad_perm:[2,3,0,1] row_mask:0xf bank_mask:0xf bound_ctrl:1
	s_nop 1
	v_add_f32_dpp v0, v0, v0 row_half_mirror row_mask:0xf bank_mask:0xf bound_ctrl:1
	s_nop 1
	v_add_f32_dpp v0, v0, v0 row_mirror row_mask:0xf bank_mask:0xf bound_ctrl:1
	s_nop 1
	v_readlane_b32 vcc_lo, v0, 0
	v_readlane_b32 vcc_hi, v0, 16
	v_readlane_b32 s8, v0, 32
	v_readlane_b32 s9, v0, 48
	s_nop 1
	v_mov_b32_e32 v0, vcc_lo
	v_add_f32_e32 v0, vcc_hi, v0
	v_add_f32_e32 v0, s8, v0
	v_add_f32_e32 v0, s9, v0
	v_mov_b32_e32 v28, v30
	v_mov_b32_e32 v29, v32
	v_mov_b32_e32 v32, v31
	v_mov_b32_e32 v46, v34
	v_mov_b32_e32 v47, v36
	v_mov_b32_e32 v36, v35
	v_mul_f32_e32 v0, 0x3a800000, v0
	v_pk_add_f32 v[30:31], v[38:39], v[0:1] op_sel_hi:[1,0] neg_lo:[0,1] neg_hi:[0,1]
	v_pk_add_f32 v[34:35], v[40:41], v[0:1] op_sel_hi:[1,0] neg_lo:[0,1] neg_hi:[0,1]
	v_pk_add_f32 v[40:41], v[44:45], v[0:1] op_sel_hi:[1,0] neg_lo:[0,1] neg_hi:[0,1]
	v_pk_mul_f32 v[44:45], v[30:31], v[30:31]
	v_pk_add_f32 v[38:39], v[42:43], v[0:1] op_sel_hi:[1,0] neg_lo:[0,1] neg_hi:[0,1]
	v_pk_add_f32 v[28:29], v[28:29], v[0:1] op_sel_hi:[1,0] neg_lo:[0,1] neg_hi:[0,1]
	v_pk_add_f32 v[42:43], v[46:47], v[0:1] op_sel_hi:[1,0] neg_lo:[0,1] neg_hi:[0,1]
	v_pk_add_f32 v[32:33], v[32:33], v[0:1] op_sel_hi:[1,0] neg_lo:[0,1] neg_hi:[0,1]
	v_pk_add_f32 v[36:37], v[36:37], v[0:1] op_sel_hi:[1,0] neg_lo:[0,1] neg_hi:[0,1]
	v_pk_mul_f32 v[46:47], v[34:35], v[34:35]
	v_add_f32_e32 v0, v44, v45
	v_add_f32_e32 v0, v46, v0
	v_pk_mul_f32 v[48:49], v[38:39], v[38:39]
	v_add_f32_e32 v0, v47, v0
	v_add_f32_e32 v0, v48, v0
	v_pk_mul_f32 v[50:51], v[40:41], v[40:41]
	v_add_f32_e32 v0, v49, v0
	v_add_f32_e32 v0, v50, v0
	v_pk_mul_f32 v[52:53], v[28:29], v[28:29]
	v_add_f32_e32 v0, v51, v0
	v_add_f32_e32 v0, v52, v0
	v_pk_mul_f32 v[54:55], v[42:43], v[42:43]
	v_add_f32_e32 v0, v53, v0
	v_add_f32_e32 v0, v54, v0
	v_pk_mul_f32 v[56:57], v[32:33], v[32:33]
	v_add_f32_e32 v0, v55, v0
	v_add_f32_e32 v0, v56, v0
	v_pk_mul_f32 v[58:59], v[36:37], v[36:37]
	v_add_f32_e32 v0, v57, v0
	v_add_f32_e32 v0, v58, v0
	v_add_f32_e32 v0, v59, v0
	s_nop 1
	v_add_f32_dpp v0, v0, v0 quad_perm:[1,0,3,2] row_mask:0xf bank_mask:0xf bound_ctrl:1
	s_nop 1
	v_add_f32_dpp v0, v0, v0 quad_perm:[2,3,0,1] row_mask:0xf bank_mask:0xf bound_ctrl:1
	s_nop 1
	v_add_f32_dpp v0, v0, v0 row_half_mirror row_mask:0xf bank_mask:0xf bound_ctrl:1
	s_nop 1
	v_add_f32_dpp v0, v0, v0 row_mirror row_mask:0xf bank_mask:0xf bound_ctrl:1
	s_nop 1
	v_readlane_b32 vcc_lo, v0, 0
	v_readlane_b32 vcc_hi, v0, 16
	v_readlane_b32 s8, v0, 32
	v_readlane_b32 s9, v0, 48
	s_nop 1
	v_mov_b32_e32 v0, vcc_lo
	v_add_f32_e32 v0, vcc_hi, v0
	v_add_f32_e32 v0, s8, v0
	v_add_f32_e32 v0, s9, v0
	v_fmamk_f32 v0, v0, 0x3a800000, v224
	v_mul_f32_e32 v3, 0x4b800000, v0
	v_cmp_gt_f32_e32 vcc, s2, v0
	s_nop 1
	v_cndmask_b32_e32 v0, v0, v3, vcc
	v_rsq_f32_e32 v0, v0
	s_nop 0
	v_mul_f32_e32 v3, 0x45800000, v0
	v_cndmask_b32_e32 v0, v0, v3, vcc
	v_pk_mul_f32 v[30:31], v[30:31], v[0:1] op_sel_hi:[1,0]
	v_pk_mul_f32 v[34:35], v[34:35], v[0:1] op_sel_hi:[1,0]
	v_pk_fma_f32 v[18:19], v[60:61], v[30:31], v[76:77]
	v_pk_fma_f32 v[20:21], v[62:63], v[34:35], v[78:79]
	v_cvt_pk_f16_f32 v18, v18, v19
	v_cvt_pk_f16_f32 v19, v20, v21
	global_store_dwordx2 v[26:27], v[18:19], off
	v_pk_mul_f32 v[30:31], v[38:39], v[0:1] op_sel_hi:[1,0]
	v_pk_mul_f32 v[34:35], v[40:41], v[0:1] op_sel_hi:[1,0]
	v_pk_mul_f32 v[28:29], v[28:29], v[0:1] op_sel_hi:[1,0]
	v_cmp_lt_i32_e32 vcc, s3, v2
	s_or_b64 s[4:5], vcc, s[4:5]
	v_pk_fma_f32 v[18:19], v[64:65], v[30:31], v[80:81]
	v_pk_fma_f32 v[20:21], v[66:67], v[34:35], v[82:83]
	v_cvt_pk_f16_f32 v18, v18, v19
	v_cvt_pk_f16_f32 v19, v20, v21
	global_store_dwordx2 v[26:27], v[18:19], off offset:512
	v_pk_mul_f32 v[30:31], v[42:43], v[0:1] op_sel_hi:[1,0]
	v_pk_fma_f32 v[18:19], v[68:69], v[28:29], v[84:85]
	v_pk_fma_f32 v[20:21], v[70:71], v[30:31], v[86:87]
	v_cvt_pk_f16_f32 v18, v18, v19
	v_cvt_pk_f16_f32 v19, v20, v21
	global_store_dwordx2 v[26:27], v[18:19], off offset:1024
	v_pk_mul_f32 v[28:29], v[32:33], v[0:1] op_sel_hi:[1,0]
	v_pk_mul_f32 v[30:31], v[36:37], v[0:1] op_sel_hi:[1,0]
	v_pk_fma_f32 v[18:19], v[72:73], v[28:29], v[88:89]
	v_pk_fma_f32 v[20:21], v[74:75], v[30:31], v[90:91]
	v_cvt_pk_f16_f32 v18, v18, v19
	v_cvt_pk_f16_f32 v19, v20, v21
	global_store_dwordx2 v[26:27], v[18:19], off offset:1536
	s_andn2_b64 exec, exec, s[4:5]
	s_cbranch_execnz .LBB0_1193
.LBB0_1194:
	s_or_b64 exec, exec, s[0:1]
	v_lshlrev_b32_e32 v18, 4, v180
	ds_read_b128 v[60:63], v18
	ds_read_b128 v[64:67], v18 offset:4096
	ds_read_b128 v[68:71], v18 offset:8192
	ds_read_b128 v[72:75], v18 offset:12288
	ds_read_b128 v[76:79], v18 offset:16384
	ds_read_b128 v[80:83], v18 offset:20480
	ds_read_b128 v[84:87], v18 offset:24576
	ds_read_b128 v[88:91], v18 offset:28672
	s_waitcnt lgkmcnt(0)
	s_waitcnt vmcnt(0)
	s_barrier
	s_and_saveexec_b64 s[0:1], s[48:49]
	s_cbranch_execz .LBB0_1231
	s_mov_b64 s[4:5], exec
	v_mbcnt_lo_u32_b32 v0, s4, 0
	v_mbcnt_hi_u32_b32 v0, s5, v0
	v_cmp_eq_u32_e32 vcc, 0, v0
	s_waitcnt vmcnt(0) expcnt(0) lgkmcnt(0)
	s_and_saveexec_b64 s[6:7], vcc
	s_cbranch_execz .LBB0_1197
	s_bcnt1_i32_b64 s2, s[4:5]
	v_mov_b32_e32 v2, s2
	v_readlane_b32 s2, v247, 8
	v_readlane_b32 s3, v247, 9
	s_nop 4
	global_atomic_add v2, v1, v2, s[2:3] sc0

; __device__ __forceinline__ int tidx() { int t = threadIdx.x; asm volatile("" : "+v"(t)); return t; }
; __device__ __forceinline__ int bidx() { int t = blockIdx.x; asm volatile("" : "+s"(t)); return t; }
; __device__ __forceinline__ void ln_phase(const h16* V, float* X, h16* Xh, const float* g, const float* b, bool final_out, bool dry = false) {
;   const int tid__ = tidx(); const int lane = tid__ & 63, wid = tid__ >> 6;
;   for (int row = bidx() * 4 + wid; row < T_; row += gridDim.x * 4) {
;     const h16* vr = V + (size_t)row * 1024;
;     f4 v[4];
;     float s = 0.f;
; #pragma unroll
;     for (int i = 0; i < 4; ++i) {
;       h4 hv = *(const h4*)(vr + i * 256 + lane * 4);
;       v[i][0] = (float)hv[0]; v[i][1] = (float)hv[1]; v[i][2] = (float)hv[2]; v[i][3] = (float)hv[3];
;       s += v[i][0] + v[i][1] + v[i][2] + v[i][3];
;     }
.LBB0_1369:
	s_or_b64 exec, exec, s[0:1]
	v_readlane_b32 s0, v248, 54
	v_readlane_b32 s8, v248, 62
	v_readlane_b32 s9, v248, 63
	v_readlane_b32 s10, v247, 0
	v_readlane_b32 s11, v247, 1
	v_readlane_b32 s8, v248, 0
	v_readlane_b32 s4, v248, 58
	v_readlane_b32 s5, v248, 59
	v_readlane_b32 s6, v248, 60
	v_readlane_b32 s7, v248, 61
	v_readlane_b32 s14, v247, 4
	v_readlane_b32 s15, v247, 5
	v_readlane_b32 s9, v248, 1
	v_readlane_b32 s1, v248, 55
	s_mov_b64 s[4:5], s[14:15]
	s_mov_b64 s[6:7], s[8:9]
	v_mov_b32_e32 v0, v180
	s_barrier
	v_readlane_b32 s0, v247, 20
	v_ashrrev_i32_e32 v2, 6, v0
	v_readlane_b32 s2, v248, 56
	v_lshl_add_u32 v2, s0, 2, v2
	v_readlane_b32 s1, v247, 21
	v_cmp_gt_i32_e32 vcc, s84, v2
	v_readlane_b32 s3, v248, 57
	v_readlane_b32 s12, v247, 2
	v_readlane_b32 s13, v247, 3
	v_readlane_b32 s10, v248, 2
	v_readlane_b32 s11, v248, 3
	v_lshlrev_b32_e32 v18, 4, v180
	ds_write_b128 v18, v[60:63]
	ds_write_b128 v18, v[64:67] offset:4096
	ds_write_b128 v18, v[68:71] offset:8192
	ds_write_b128 v18, v[72:75] offset:12288
	ds_write_b128 v18, v[76:79] offset:16384
	ds_write_b128 v18, v[80:83] offset:20480
	ds_write_b128 v18, v[84:87] offset:24576
	ds_write_b128 v18, v[88:91] offset:28672
	s_and_saveexec_b64 s[0:1], vcc
	s_mov_b32 s2, 0x800000
	s_cbranch_execz .LBB0_1372
	v_and_b32_e32 v6, 64, v230
	v_add_u32_e32 v6, 64, v6
	v_xor_b32_e32 v7, 32, v230
	v_cmp_lt_i32_e32 vcc, v7, v6
	s_add_i32 s88, s16, 0x400
	s_lshl_b64 s[8:9], s[88:89], 2
	v_cndmask_b32_e32 v7, v230, v7, vcc
	v_lshlrev_b32_e32 v12, 2, v7
	v_xor_b32_e32 v7, 16, v230
	v_cmp_lt_i32_e32 vcc, v7, v6
	s_add_u32 s6, s6, s8
	s_addc_u32 s7, s7, s9
	v_cndmask_b32_e32 v7, v230, v7, vcc
	v_lshlrev_b32_e32 v13, 2, v7
	v_xor_b32_e32 v7, 8, v230
	v_cmp_lt_i32_e32 vcc, v7, v6
	v_lshlrev_b32_e32 v0, 2, v0
	s_add_u32 s4, s4, s8
	v_cndmask_b32_e32 v7, v230, v7, vcc
	v_lshlrev_b32_e32 v14, 2, v7
	v_xor_b32_e32 v7, 4, v230
	v_cmp_lt_i32_e32 vcc, v7, v6
	v_and_b32_e32 v3, 0xfc, v0
	s_addc_u32 s5, s5, s9
	v_cndmask_b32_e32 v7, v230, v7, vcc
	v_lshlrev_b32_e32 v15, 2, v7
	v_xor_b32_e32 v7, 2, v230
	v_cmp_lt_i32_e32 vcc, v7, v6
	v_lshlrev_b32_e32 v8, 2, v3
	v_mov_b32_e32 v9, v1
	v_cndmask_b32_e32 v7, v230, v7, vcc
	v_lshlrev_b32_e32 v16, 2, v7
	v_xor_b32_e32 v7, 1, v230
	v_cmp_lt_i32_e32 vcc, v7, v6
	v_lshlrev_b32_e32 v0, 1, v3
	s_mov_b32 s88, 0xfffffc0
	v_cndmask_b32_e32 v6, v230, v7, vcc
	v_lshlrev_b32_e32 v17, 2, v6
	v_lshl_add_u64 v[6:7], s[4:5], 0, v[8:9]
	v_readlane_b32 s4, v247, 48
	v_readlane_b32 s5, v247, 49
	v_lshl_add_u64 v[4:5], s[34:35], 0, v[0:1]
	v_lshl_add_u64 v[8:9], s[6:7], 0, v[8:9]
	v_lshl_add_u64 v[10:11], s[4:5], 0, v[0:1]
	s_mov_b64 s[4:5], 0
	global_load_dwordx4 v[60:63], v[6:7], off
	global_load_dwordx4 v[64:67], v[6:7], off offset:1024
	global_load_dwordx4 v[68:71], v[6:7], off offset:2048
	global_load_dwordx4 v[72:75], v[6:7], off offset:3072
	global_load_dwordx4 v[76:79], v[8:9], off
	global_load_dwordx4 v[80:83], v[8:9], off offset:1024
	global_load_dwordx4 v[84:87], v[8:9], off offset:2048
	global_load_dwordx4 v[88:91], v[8:9], off offset:3072
	s_waitcnt vmcnt(0)
; __device__ __forceinline__ int bidx() { int t = blockIdx.x; asm volatile("" : "+s"(t)); return t; }
; __device__ __forceinline__ void ln_phase(const h16* V, float* X, h16* Xh, const float* g, const float* b, bool final_out, bool dry = false) {
;     ...
;   for (int row = bidx() * 4 + wid; row < T_; row += gridDim.x * 4) {
;     const h16* vr = V + (size_t)row * 1024;
;     f4 v[4];
;     float s = 0.f;
; #pragma unroll
;     for (int i = 0; i < 4; ++i) {
;       h4 hv = *(const h4*)(vr + i * 256 + lane * 4);
;       v[i][0] = (float)hv[0]; v[i][1] = (float)hv[1]; v[i][2] = (float)hv[2]; v[i][3] = (float)hv[3];
;       s += v[i][0] + v[i][1] + v[i][2] + v[i][3];
;     }
;     for (int o = 32; o > 0; o >>= 1) s += __shfl_xor(s, o);
;     const float mu = s * (1.f / 1024.f);
;     float q = 0.f;
; #pragma unroll
;     for (int i = 0; i < 4; ++i)
; #pragma unroll
;       for (int j = 0; j < 4; ++j) { float d = v[i][j] - mu; q += d * d; }
;     for (int o = 32; o > 0; o >>= 1) q += __shfl_xor(q, o);
;     const float rs = rsqrtf(q * (1.f / 1024.f) + 1e-5f);
;     if (dry && rs != 12345.678f) continue;
; #pragma unroll
;     for (int i = 0; i < 4; ++i) {
;       int c = i * 256 + lane * 4;
;       f4 gg = *(const f4*)(g + c), bb = *(const f4*)(b + c), o;
;       h4 oh;
; #pragma unroll
;       for (int j = 0; j < 4; ++j) { o[j] = (v[i][j] - mu) * rs * gg[j] + bb[j]; oh[j] = (h16)o[j]; }
;       if (final_out) *(f4*)(X + (size_t)row * 1024 + c) = o;
;       else *(h4*)(Xh + (size_t)row * 1024 + c) = oh;
;     }
.LBB0_1371:
	v_ashrrev_i32_e32 v3, 31, v2
	v_lshlrev_b64 v[26:27], 11, v[2:3]
	v_lshl_add_u64 v[18:19], v[4:5], 0, v[26:27]
	global_load_dwordx2 v[20:21], v[18:19], off offset:1536
	global_load_dwordx2 v[22:23], v[18:19], off offset:1024
	global_load_dwordx2 v[24:25], v[18:19], off
	s_nop 0
	global_load_dwordx2 v[18:19], v[18:19], off offset:512
	v_mov_b32_e32 v28, v1
	v_lshl_add_u64 v[26:27], v[10:11], 0, v[26:27]
	v_add_u32_e32 v2, s77, v2
	s_waitcnt vmcnt(3)
	v_cvt_f32_f16_e32 v31, v20
	s_waitcnt vmcnt(2)
	v_cvt_f32_f16_e32 v30, v22
	s_waitcnt vmcnt(1)
	v_cvt_f32_f16_sdwa v39, v24 dst_sel:DWORD dst_unused:UNUSED_PAD src0_sel:WORD_1
	v_cvt_f32_f16_e32 v38, v24
	v_cvt_f32_f16_e32 v40, v25
	s_waitcnt vmcnt(0)
	v_cvt_f32_f16_e32 v42, v18
	v_cvt_f32_f16_sdwa v43, v18 dst_sel:DWORD dst_unused:UNUSED_PAD src0_sel:WORD_1
	v_cvt_f32_f16_sdwa v41, v25 dst_sel:DWORD dst_unused:UNUSED_PAD src0_sel:WORD_1
	v_cvt_f32_f16_e32 v44, v19
	v_cvt_f32_f16_sdwa v45, v19 dst_sel:DWORD dst_unused:UNUSED_PAD src0_sel:WORD_1
	v_cvt_f32_f16_sdwa v33, v20 dst_sel:DWORD dst_unused:UNUSED_PAD src0_sel:WORD_1
	v_cvt_f32_f16_sdwa v32, v22 dst_sel:DWORD dst_unused:UNUSED_PAD src0_sel:WORD_1
	v_mov_b32_e32 v0, v39
	v_cvt_f32_f16_e32 v35, v21
	v_cvt_f32_f16_e32 v34, v23
	v_pk_add_f32 v[24:25], v[0:1], v[38:39]
	v_cvt_f32_f16_sdwa v37, v21 dst_sel:DWORD dst_unused:UNUSED_PAD src0_sel:WORD_1
	v_cvt_f32_f16_sdwa v36, v23 dst_sel:DWORD dst_unused:UNUSED_PAD src0_sel:WORD_1
	v_mov_b32_e32 v20, v40
	v_mov_b32_e32 v21, v43
	v_mov_b32_e32 v25, v42
	v_pk_mov_b32 v[22:23], v[40:41], v[44:45] op_sel:[1,0]
	v_pk_add_f32 v[20:21], v[24:25], v[20:21]
	v_pk_add_f32 v[18:19], v[30:31], v[32:33]
	v_mov_b32_e32 v29, v45
	v_pk_add_f32 v[20:21], v[20:21], v[22:23]
	v_pk_add_f32 v[18:19], v[18:19], v[34:35]
	v_pk_add_f32 v[20:21], v[20:21], v[28:29]
	v_pk_add_f32 v[18:19], v[18:19], v[36:37]
	v_add_f32_e32 v0, v20, v21
	v_add_f32_e32 v0, v0, v18
	v_add_f32_e32 v0, v0, v19
	s_nop 1
	v_add_f32_dpp v0, v0, v0 quad_perm:[1,0,3,2] row_mask:0xf bank_mask:0xf bound_ctrl:1
	s_nop 1
	v_add_f32_dpp v0, v0, v0 quad_perm:[2,3,0,1] row_mask:0xf bank_mask:0xf bound_ctrl:1
	s_nop 1
	v_add_f32_dpp v0, v0, v0 row_half_mirror row_mask:0xf bank_mask:0xf bound_ctrl:1
	s_nop 1
	v_add_f32_dpp v0, v0, v0 row_mirror row_mask:0xf bank_mask:0xf bound_ctrl:1
	s_nop 1
	v_readlane_b32 vcc_lo, v0, 0
	v_readlane_b32 vcc_hi, v0, 16
	v_readlane_b32 s8, v0, 32
	v_readlane_b32 s9, v0, 48
	s_nop 1
	v_mov_b32_e32 v0, vcc_lo
	v_add_f32_e32 v0, vcc_hi, v0
	v_add_f32_e32 v0, s8, v0
	v_add_f32_e32 v0, s9, v0
	v_mov_b32_e32 v28, v30
	v_mov_b32_e32 v29, v32
	v_mov_b32_e32 v32, v31
	v_mov_b32_e32 v46, v34
	v_mov_b32_e32 v47, v36
	v_mov_b32_e32 v36, v35
	v_mul_f32_e32 v0, 0x3a800000, v0
	v_pk_add_f32 v[30:31], v[38:39], v[0:1] op_sel_hi:[1,0] neg_lo:[0,1] neg_hi:[0,1]
	v_pk_add_f32 v[34:35], v[40:41], v[0:1] op_sel_hi:[1,0] neg_lo:[0,1] neg_hi:[0,1]
	v_pk_add_f32 v[40:41], v[44:45], v[0:1] op_sel_hi:[1,0] neg_lo:[0,1] neg_hi:[0,1]
	v_pk_mul_f32 v[44:45], v[30:31], v[30:31]
	v_pk_add_f32 v[38:39], v[42:43], v[0:1] op_sel_hi:[1,0] neg_lo:[0,1] neg_hi:[0,1]
	v_pk_add_f32 v[28:29], v[28:29], v[0:1] op_sel_hi:[1,0] neg_lo:[0,1] neg_hi:[0,1]
	v_pk_add_f32 v[42:43], v[46:47], v[0:1] op_sel_hi:[1,0] neg_lo:[0,1] neg_hi:[0,1]
	v_pk_add_f32 v[32:33], v[32:33], v[0:1] op_sel_hi:[1,0] neg_lo:[0,1] neg_hi:[0,1]
	v_pk_add_f32 v[36:37], v[36:37], v[0:1] op_sel_hi:[1,0] neg_lo:[0,1] neg_hi:[0,1]
	v_pk_mul_f32 v[46:47], v[34:35], v[34:35]
	v_add_f32_e32 v0, v44, v45
	v_add_f32_e32 v0, v46, v0
	v_pk_mul_f32 v[48:49], v[38:39], v[38:39]
	v_add_f32_e32 v0, v47, v0
	v_add_f32_e32 v0, v48, v0
	v_pk_mul_f32 v[50:51], v[40:41], v[40:41]
	v_add_f32_e32 v0, v49, v0
	v_add_f32_e32 v0, v50, v0
	v_pk_mul_f32 v[52:53], v[28:29], v[28:29]
	v_add_f32_e32 v0, v51, v0
	v_add_f32_e32 v0, v52, v0
	v_pk_mul_f32 v[54:55], v[42:43], v[42:43]
	v_add_f32_e32 v0, v53, v0
	v_add_f32_e32 v0, v54, v0
	v_pk_mul_f32 v[56:57], v[32:33], v[32:33]
	v_add_f32_e32 v0, v55, v0
	v_add_f32_e32 v0, v56, v0
	v_pk_mul_f32 v[58:59], v[36:37], v[36:37]
	v_add_f32_e32 v0, v57, v0
	v_add_f32_e32 v0, v58, v0
	v_add_f32_e32 v0, v59, v0
	s_nop 1
	v_add_f32_dpp v0, v0, v0 quad_perm:[1,0,3,2] row_mask:0xf bank_mask:0xf bound_ctrl:1
	s_nop 1
	v_add_f32_dpp v0, v0, v0 quad_perm:[2,3,0,1] row_mask:0xf bank_mask:0xf bound_ctrl:1
	s_nop 1
	v_add_f32_dpp v0, v0, v0 row_half_mirror row_mask:0xf bank_mask:0xf bound_ctrl:1
	s_nop 1
	v_add_f32_dpp v0, v0, v0 row_mirror row_mask:0xf bank_mask:0xf bound_ctrl:1
	s_nop 1
	v_readlane_b32 vcc_lo, v0, 0
	v_readlane_b32 vcc_hi, v0, 16
	v_readlane_b32 s8, v0, 32
	v_readlane_b32 s9, v0, 48
	s_nop 1
	v_mov_b32_e32 v0, vcc_lo
	v_add_f32_e32 v0, vcc_hi, v0
	v_add_f32_e32 v0, s8, v0
	v_add_f32_e32 v0, s9, v0
	v_fmamk_f32 v0, v0, 0x3a800000, v224
	v_mul_f32_e32 v3, 0x4b800000, v0
	v_cmp_gt_f32_e32 vcc, s2, v0
	s_nop 1
	v_cndmask_b32_e32 v0, v0, v3, vcc
	v_rsq_f32_e32 v0, v0
	s_nop 0
	v_mul_f32_e32 v3, 0x45800000, v0
	v_cndmask_b32_e32 v0, v0, v3, vcc
	v_pk_mul_f32 v[30:31], v[30:31], v[0:1] op_sel_hi:[1,0]
	v_pk_mul_f32 v[34:35], v[34:35], v[0:1] op_sel_hi:[1,0]
	v_pk_fma_f32 v[18:19], v[60:61], v[30:31], v[76:77]
	v_pk_fma_f32 v[20:21], v[62:63], v[34:35], v[78:79]
	v_cvt_pk_f16_f32 v18, v18, v19
	v_cvt_pk_f16_f32 v19, v20, v21
	global_store_dwordx2 v[26:27], v[18:19], off
	v_pk_mul_f32 v[30:31], v[38:39], v[0:1] op_sel_hi:[1,0]
	v_pk_mul_f32 v[34:35], v[40:41], v[0:1] op_sel_hi:[1,0]
	v_pk_mul_f32 v[28:29], v[28:29], v[0:1] op_sel_hi:[1,0]
	v_cmp_lt_i32_e32 vcc, s17, v2
	s_or_b64 s[4:5], vcc, s[4:5]
	v_pk_fma_f32 v[18:19], v[64:65], v[30:31], v[80:81]
	v_pk_fma_f32 v[20:21], v[66:67], v[34:35], v[82:83]
	v_cvt_pk_f16_f32 v18, v18, v19
	v_cvt_pk_f16_f32 v19, v20, v21
	global_store_dwordx2 v[26:27], v[18:19], off offset:512
	v_pk_mul_f32 v[30:31], v[42:43], v[0:1] op_sel_hi:[1,0]
	v_pk_fma_f32 v[18:19], v[68:69], v[28:29], v[84:85]
	v_pk_fma_f32 v[20:21], v[70:71], v[30:31], v[86:87]
	v_cvt_pk_f16_f32 v18, v18, v19
	v_cvt_pk_f16_f32 v19, v20, v21
	global_store_dwordx2 v[26:27], v[18:19], off offset:1024
	v_pk_mul_f32 v[28:29], v[32:33], v[0:1] op_sel_hi:[1,0]
	v_pk_mul_f32 v[30:31], v[36:37], v[0:1] op_sel_hi:[1,0]
	v_pk_fma_f32 v[18:19], v[72:73], v[28:29], v[88:89]
	v_pk_fma_f32 v[20:21], v[74:75], v[30:31], v[90:91]
	v_cvt_pk_f16_f32 v18, v18, v19
	v_cvt_pk_f16_f32 v19, v20, v21
	global_store_dwordx2 v[26:27], v[18:19], off offset:1536
	s_andn2_b64 exec, exec, s[4:5]
	s_cbranch_execnz .LBB0_1371
